# v68 + dn_pre unit: K/V tile loads and c_alog load hoisted to the unit start (single global round trip)
# speedup vs baseline: 1.0067x; 1.0063x over previous
.LBB0_397:
	s_waitcnt vmcnt(0)
	v_mov_b32_e32 v0, v168
	s_lshl_b32 s51, s40, 2
	s_and_b32 s52, s40, 1
	v_readfirstlane_b32 s53, v0
	s_bfe_u32 s50, s40, 0x30001
	s_andn2_b32 s51, s51, 63
	v_ashrrev_i32_e32 v44, 2, v0
	s_cmp_eq_u32 s52, 0
	s_cselect_b64 s[36:37], -1, 0
	v_sub_u32_e32 v45, 63, v44
	v_cndmask_b32_e64 v45, v45, v44, s[36:37]
	v_add_u32_e32 v46, s51, v45
	v_ashrrev_i32_e32 v47, 31, v46
	v_readlane_b32 s2, v253, 7
	v_lshlrev_b64 v[46:47], 10, v[46:47]
	v_readlane_b32 s3, v253, 8
	v_lshlrev_b32_e32 v48, 4, v0
	s_lshl_b32 s30, s50, 7
	v_lshl_add_u64 v[50:51], s[2:3], 0, v[46:47]
	v_readlane_b32 s2, v252, 51
	v_readlane_b32 s3, v252, 52
	v_and_b32_e32 v48, 48, v48
	v_lshl_add_u64 v[50:51], v[50:51], 0, s[30:31]
	v_lshl_add_u64 v[46:47], s[2:3], 0, v[46:47]
	v_lshlrev_b32_e32 v48, 1, v48
	v_mov_b32_e32 v49, v2
	v_lshl_add_u64 v[46:47], v[46:47], 0, s[30:31]
	v_lshl_add_u64 v[50:51], v[50:51], 0, v[48:49]
	v_lshl_add_u64 v[46:47], v[46:47], 0, v[48:49]
	global_load_dwordx4 v[60:63], v[50:51], off offset:16
	global_load_dwordx4 v[64:67], v[50:51], off
	global_load_dwordx4 v[68:71], v[46:47], off offset:16
	global_load_dwordx4 v[72:75], v[46:47], off
	v_cmp_gt_i32_e32 vcc, 64, v0
	s_waitcnt lgkmcnt(0)
	s_barrier
	s_and_saveexec_b64 s[42:43], vcc
	s_cbranch_execz .LBB0_403
	s_cmp_eq_u32 s52, 0
	s_cselect_b64 s[36:37], -1, 0
	v_sub_u32_e32 v1, 63, v0
	v_cndmask_b32_e64 v1, v1, v0, s[36:37]
	v_add_u32_e32 v4, s51, v1
	v_ashrrev_i32_e32 v5, 31, v4
	v_readlane_b32 s18, v253, 15
	v_lshlrev_b64 v[4:5], 7, v[4:5]
	v_readlane_b32 s19, v253, 16
	s_lshl_b32 s2, s52, 3
	s_lshl_b32 s30, s52, 5
	v_lshl_add_u64 v[4:5], s[18:19], 0, v[4:5]
	v_readlane_b32 s18, v255, 3
	s_or_b32 s2, s2, s18
	s_or_b32 s20, s2, s50
	s_ashr_i32 s21, s20, 31
	v_readlane_b32 s80, v250, 17
	v_lshl_add_u64 v[4:5], v[4:5], 0, s[30:31]
	s_lshl_b32 s30, s50, 2
	s_lshl_b64 s[44:45], s[20:21], 2
	v_readlane_b32 s94, v250, 31
	v_readlane_b32 s95, v250, 32
	s_add_u32 s20, s94, s44
	v_lshl_add_u64 v[4:5], v[4:5], 0, s[30:31]
	s_addc_u32 s21, s95, s45
	global_load_dword v1, v[4:5], off
	global_load_dword v3, v[4:5], off offset:64
	s_mov_b32 s2, 0x41700000
	global_load_dword v4, v2, s[20:21]
	s_add_u32 s46, s92, s44
	s_addc_u32 s47, s93, s45
	global_load_dword v76, v2, s[46:47]
	v_readlane_b32 s19, v255, 4
	v_readlane_b32 s81, v250, 18
	v_readlane_b32 s82, v250, 19
	v_readlane_b32 s83, v250, 20
	v_readlane_b32 s84, v250, 21
	v_readlane_b32 s85, v250, 22
	v_readlane_b32 s86, v250, 23
	v_readlane_b32 s87, v250, 24
	v_readlane_b32 s88, v250, 25
	v_readlane_b32 s89, v250, 26
	v_readlane_b32 s90, v250, 27
	v_readlane_b32 s91, v250, 28
	v_readlane_b32 s92, v250, 29
	v_readlane_b32 s93, v250, 30
	s_waitcnt vmcnt(0)
	v_add_f32_e32 v1, v1, v4
	v_cmp_nlt_f32_e64 s[36:37], s2, v1
	s_and_saveexec_b64 s[46:47], s[36:37]
	s_cbranch_execz .LBB0_402
	v_mul_f32_e32 v4, 0x3fb8aa3b, v1
	v_exp_f32_e32 v4, v4
	s_mov_b32 s2, 0xc1200000
	v_cmp_ngt_f32_e64 s[36:37], s2, v1
	s_and_saveexec_b64 s[48:49], s[36:37]
	s_cbranch_execz .LBB0_401
	v_add_f32_e32 v1, 1.0, v4
	s_mov_b32 s2, 0x800000
	v_cmp_gt_f32_e64 s[36:37], s2, v1
	s_mov_b32 s2, 0x3f317217
	s_mov_b32 s1, 0x7f800000
	v_cndmask_b32_e64 v4, 0, 32, s[36:37]
	v_ldexp_f32 v1, v1, v4
	v_log_f32_e32 v1, v1
	s_nop 0
	v_mul_f32_e32 v4, 0x3f317217, v1
	v_fma_f32 v4, v1, s2, -v4
	v_fmac_f32_e32 v4, 0x3377d1cf, v1
	v_fmac_f32_e32 v4, 0x3f317217, v1
	v_cmp_lt_f32_e64 s[38:39], |v1|, s1
	s_nop 1
	v_cndmask_b32_e64 v1, v1, v4, s[38:39]
	v_cndmask_b32_e64 v4, 0, v173, s[36:37]
	v_sub_f32_e32 v4, v1, v4

.LBB0_402:
	s_or_b64 exec, exec, s[46:47]
	v_readlane_b32 s80, v250, 17
	v_readlane_b32 s92, v250, 29
	v_readlane_b32 s93, v250, 30
	s_add_u32 s20, s92, s44
	s_addc_u32 s21, s93, s45
	v_add_u32_e32 v6, -1, v179
	v_cmp_lt_i32_e64 s[36:37], v6, v181
	v_mul_f32_e32 v3, 0xbfb8aa3b, v3
	v_exp_f32_e32 v3, v3
	v_cndmask_b32_e64 v6, v6, v179, s[36:37]
	v_lshlrev_b32_e32 v6, 2, v6
	v_cmp_gt_i32_e64 s[36:37], 1, v0
	v_add_f32_e32 v3, 1.0, v3
	v_rcp_f32_e32 v3, v3
	s_ashr_i32 s41, s40, 31
	s_lshl_b64 s[20:21], s[40:41], 8
	v_readlane_b32 s2, v253, 11
	v_readlane_b32 s3, v253, 12
	s_add_u32 s20, s2, s20
	s_addc_u32 s21, s3, s21
	v_readlane_b32 s81, v250, 18
	v_readlane_b32 s82, v250, 19
	v_readlane_b32 s83, v250, 20
	v_readlane_b32 s84, v250, 21
	v_readlane_b32 s85, v250, 22
	v_readlane_b32 s86, v250, 23
	v_readlane_b32 s87, v250, 24
	v_readlane_b32 s88, v250, 25
	v_readlane_b32 s89, v250, 26
	v_readlane_b32 s90, v250, 27
	v_readlane_b32 s91, v250, 28
	v_readlane_b32 s94, v250, 31
	v_readlane_b32 s95, v250, 32
	v_mul_f32_e32 v4, 0x3fb8aa3b, v76
	v_exp_f32_e32 v4, v4
	s_nop 0
	v_mul_f32_e64 v5, v1, -v4
	ds_bpermute_b32 v6, v6, v5
	s_waitcnt lgkmcnt(0)
	v_fma_f32 v1, v1, -v4, v6
	v_add_u32_e32 v4, -2, v179
	v_cndmask_b32_e64 v1, v1, v5, s[36:37]
	v_cmp_lt_i32_e64 s[36:37], v4, v181
	s_nop 1
	v_cndmask_b32_e64 v4, v4, v179, s[36:37]
	v_lshlrev_b32_e32 v4, 2, v4
	ds_bpermute_b32 v4, v4, v1
	v_cmp_gt_i32_e64 s[36:37], 2, v0
	s_waitcnt lgkmcnt(0)
	v_add_f32_e32 v4, v1, v4
	v_cndmask_b32_e64 v1, v4, v1, s[36:37]
	v_add_u32_e32 v4, -4, v179
	v_cmp_lt_i32_e64 s[36:37], v4, v181
	s_nop 1
	v_cndmask_b32_e64 v4, v4, v179, s[36:37]
	v_lshlrev_b32_e32 v4, 2, v4
	ds_bpermute_b32 v4, v4, v1
	v_cmp_gt_i32_e64 s[36:37], 4, v0
	s_waitcnt lgkmcnt(0)
	v_add_f32_e32 v4, v1, v4
	v_cndmask_b32_e64 v1, v4, v1, s[36:37]
	v_add_u32_e32 v4, -8, v179
	v_cmp_lt_i32_e64 s[36:37], v4, v181
	s_nop 1
	v_cndmask_b32_e64 v4, v4, v179, s[36:37]
	v_lshlrev_b32_e32 v4, 2, v4
	ds_bpermute_b32 v4, v4, v1
	v_cmp_gt_i32_e64 s[36:37], 8, v0
	s_waitcnt lgkmcnt(0)
	v_add_f32_e32 v4, v1, v4
	v_cndmask_b32_e64 v1, v4, v1, s[36:37]
	v_add_u32_e32 v4, -16, v179
	v_cmp_lt_i32_e64 s[36:37], v4, v181
	s_nop 1
	v_cndmask_b32_e64 v4, v4, v179, s[36:37]
	v_lshlrev_b32_e32 v4, 2, v4
	ds_bpermute_b32 v4, v4, v1
	v_cmp_gt_i32_e64 s[36:37], 16, v0
	s_waitcnt lgkmcnt(0)
	v_add_f32_e32 v4, v1, v4
	v_cndmask_b32_e64 v1, v4, v1, s[36:37]
	v_subrev_u32_e32 v4, 32, v179
	v_cmp_lt_i32_e64 s[36:37], v4, v181
	s_nop 1
	v_cndmask_b32_e64 v4, v4, v179, s[36:37]
	v_lshlrev_b32_e32 v4, 2, v4
	ds_bpermute_b32 v4, v4, v1
	v_cmp_gt_i32_e64 s[36:37], 32, v0
	s_waitcnt lgkmcnt(0)
	v_add_f32_e32 v4, v1, v4
	v_cndmask_b32_e64 v6, v4, v1, s[36:37]
	v_ashrrev_i32_e32 v1, 31, v0
	v_lshlrev_b32_e32 v4, 2, v0
	ds_write2st64_b32 v4, v6, v3 offset0:216 offset1:217
	v_lshl_add_u64 v[4:5], v[0:1], 2, s[20:21]
	global_store_dword v[4:5], v6, off
.LBB0_403:
	s_or_b64 exec, exec, s[42:43]
	s_ashr_i32 s41, s53, 6
	v_ashrrev_i32_e32 v23, 2, v0
	s_cmp_eq_u32 s52, 0
	s_cselect_b64 s[36:37], -1, 0
	v_sub_u32_e32 v4, 63, v23
	v_cndmask_b32_e64 v4, v4, v23, s[36:37]
	v_add_u32_e32 v4, s51, v4
	v_ashrrev_i32_e32 v5, 31, v4
	v_readlane_b32 s2, v253, 7
	v_lshlrev_b64 v[4:5], 10, v[4:5]
	v_readlane_b32 s3, v253, 8
	v_lshlrev_b32_e32 v30, 4, v0
	s_lshl_b32 s30, s50, 7
	v_lshl_add_u64 v[6:7], s[2:3], 0, v[4:5]
	v_readlane_b32 s2, v252, 51
	v_readlane_b32 s3, v252, 52
	v_and_b32_e32 v24, 48, v30
	v_lshl_add_u64 v[6:7], v[6:7], 0, s[30:31]
	v_lshl_add_u64 v[4:5], s[2:3], 0, v[4:5]
	v_lshlrev_b32_e32 v20, 1, v24
	v_mov_b32_e32 v21, v2
	v_lshl_add_u64 v[4:5], v[4:5], 0, s[30:31]
	v_lshl_add_u64 v[8:9], v[6:7], 0, v[20:21]
	v_lshl_add_u64 v[16:17], v[4:5], 0, v[20:21]
	s_waitcnt lgkmcnt(0)
	s_barrier
	s_waitcnt vmcnt(0)
	v_mov_b32_e32 v4, v60
	v_mov_b32_e32 v5, v61
	v_mov_b32_e32 v6, v62
	v_mov_b32_e32 v7, v63
	v_mov_b32_e32 v8, v64
	v_mov_b32_e32 v9, v65
	v_mov_b32_e32 v10, v66
	v_mov_b32_e32 v11, v67
	v_mov_b32_e32 v12, v68
	v_mov_b32_e32 v13, v69
	v_mov_b32_e32 v14, v70
	v_mov_b32_e32 v15, v71
	v_mov_b32_e32 v16, v72
	v_mov_b32_e32 v17, v73
	v_mov_b32_e32 v18, v74
	v_mov_b32_e32 v19, v75
	s_movk_i32 s1, 0x90
	v_mul_lo_u32 v22, v23, s1
	v_add_u32_e32 v20, v22, v20
	s_movk_i32 s2, 0xff74
	v_bfe_u32 v1, v0, 4, 2
	v_and_b32_e32 v3, 15, v0
	s_cmp_gt_i32 s41, 9
	v_lshlrev_b32_e32 v31, 2, v1
	s_waitcnt vmcnt(2)
	ds_write_b128 v20, v[8:11] offset:55808
	ds_write_b128 v20, v[4:7] offset:55824
	v_mad_u64_u32 v[20:21], s[20:21], v23, s2, v[22:23]
	ds_read2st64_b32 v[20:21], v20 offset0:216 offset1:217
	s_waitcnt vmcnt(0)
	v_lshlrev_b32_e32 v22, 16, v16
	s_waitcnt lgkmcnt(0)
	v_mul_f32_e32 v20, 0x3fb8aa3b, v20
	v_exp_f32_e32 v20, v20
	v_mov_b32_e32 v32, v21
	v_mul_f32_e32 v28, v21, v20
	v_mul_lo_u32 v20, v23, s33
	v_and_b32_e32 v23, 0xffff0000, v16
	v_lshl_add_u32 v29, v24, 2, v20
	v_pk_mul_f32 v[20:21], v[32:33], v[22:23] op_sel_hi:[0,1]
	v_lshlrev_b32_e32 v22, 16, v8
	v_and_b32_e32 v23, 0xffff0000, v8
	v_lshlrev_b32_e32 v8, 16, v9
	v_and_b32_e32 v9, 0xffff0000, v9
	v_lshlrev_b32_e32 v16, 16, v17
	v_and_b32_e32 v17, 0xffff0000, v17
	v_pk_mul_f32 v[26:27], v[28:29], v[8:9] op_sel_hi:[0,1]
	v_lshlrev_b32_e32 v8, 16, v18
	v_and_b32_e32 v9, 0xffff0000, v18
	v_pk_mul_f32 v[24:25], v[28:29], v[22:23] op_sel_hi:[0,1]
	v_pk_mul_f32 v[22:23], v[32:33], v[16:17] op_sel_hi:[0,1]
	v_pk_mul_f32 v[16:17], v[32:33], v[8:9] op_sel_hi:[0,1]
	v_lshlrev_b32_e32 v8, 16, v10
	v_and_b32_e32 v9, 0xffff0000, v10
	v_lshlrev_b32_e32 v10, 16, v11
	v_and_b32_e32 v11, 0xffff0000, v11
	v_pk_mul_f32 v[8:9], v[28:29], v[8:9] op_sel_hi:[0,1]
	v_lshlrev_b32_e32 v18, 16, v19
	v_and_b32_e32 v19, 0xffff0000, v19
	v_pk_mul_f32 v[10:11], v[28:29], v[10:11] op_sel_hi:[0,1]
	v_pk_mul_f32 v[18:19], v[32:33], v[18:19] op_sel_hi:[0,1]
	ds_write_b128 v29, v[8:11] offset:272
	v_lshlrev_b32_e32 v10, 16, v4
	v_and_b32_e32 v11, 0xffff0000, v4
	ds_write_b128 v29, v[16:19] offset:16
	v_lshlrev_b32_e32 v8, 16, v12
	v_and_b32_e32 v9, 0xffff0000, v12
	v_pk_mul_f32 v[16:17], v[28:29], v[10:11] op_sel_hi:[0,1]
	v_lshlrev_b32_e32 v10, 16, v13
	v_and_b32_e32 v11, 0xffff0000, v13
	v_lshlrev_b32_e32 v4, 16, v5
	v_and_b32_e32 v5, 0xffff0000, v5
	v_pk_mul_f32 v[8:9], v[32:33], v[8:9] op_sel_hi:[0,1]
	v_pk_mul_f32 v[10:11], v[32:33], v[10:11] op_sel_hi:[0,1]
	v_pk_mul_f32 v[18:19], v[28:29], v[4:5] op_sel_hi:[0,1]
	v_lshlrev_b32_e32 v4, 16, v14
	v_and_b32_e32 v5, 0xffff0000, v14
	ds_write_b128 v29, v[8:11] offset:32
	v_pk_mul_f32 v[8:9], v[32:33], v[4:5] op_sel_hi:[0,1]
	v_lshlrev_b32_e32 v4, 16, v6
	v_and_b32_e32 v5, 0xffff0000, v6
	v_lshlrev_b32_e32 v10, 16, v15
	v_and_b32_e32 v11, 0xffff0000, v15
	v_lshlrev_b32_e32 v6, 16, v7
	v_and_b32_e32 v7, 0xffff0000, v7
	v_pk_mul_f32 v[4:5], v[28:29], v[4:5] op_sel_hi:[0,1]
	v_pk_mul_f32 v[10:11], v[32:33], v[10:11] op_sel_hi:[0,1]
	v_pk_mul_f32 v[6:7], v[28:29], v[6:7] op_sel_hi:[0,1]
	ds_write_b128 v29, v[20:23]
	ds_write_b128 v29, v[24:27] offset:256
	ds_write_b128 v29, v[16:19] offset:288
	ds_write_b128 v29, v[8:11] offset:48
	ds_write_b128 v29, v[4:7] offset:304
	s_waitcnt lgkmcnt(0)
	s_barrier
	s_cbranch_scc1 .LBB0_417
	v_lshlrev_b32_e32 v8, 4, v1
	s_mov_b32 s20, s41
	s_branch .LBB0_406
